# adds phase-0 silu(c) staging rewrite: 68 one-load-per-trip round trips replaced by two batches of 34 loads (same per-element arithmetic)
# speedup vs baseline: 1.0118x; 1.0070x over previous
; __device__ __forceinline__ void phase0(CArgs a, LAS unsigned char* lds, int tid, int lane, int wave, int G, int bx) {
;     ...
;             __syncthreads();
;             for (int idx = tid; idx < NB * 1024; idx += 512) { const int r = idx >> 10, k = idx & 1023;
;                 const float c = r < 2 ? a->in[7][r * D + half * 1024 + k] : a->in[8][(r - 2) * D + half * 1024 + k];
;                 S[idx] = c / (1.0f + __expf(-c)); }
.LBB0_835:
	s_waitcnt vmcnt(0)
	s_barrier
	s_and_saveexec_b64 s[4:5], s[38:39]
	s_cbranch_execz .LBB0_842
	s_load_dwordx2 s[16:17], s[92:93], 0x38
	s_load_dwordx2 s[44:45], s[92:93], 0x40
	v_add_u32_e32 v42, s14, v164
	v_lshlrev_b32_e32 v42, 2, v42
	v_mov_b32_e32 v34, v179
	s_waitcnt lgkmcnt(0)
	s_add_u32 s46, s16, 0x0
	s_addc_u32 s47, s17, 0
	global_load_dword v206, v42, s[46:47]
	s_add_u32 s46, s16, 0x800
	s_addc_u32 s47, s17, 0
	global_load_dword v207, v42, s[46:47]
	s_add_u32 s46, s16, 0x2000
	s_addc_u32 s47, s17, 0
	global_load_dword v208, v42, s[46:47]
	s_add_u32 s46, s16, 0x2800
	s_addc_u32 s47, s17, 0
	global_load_dword v209, v42, s[46:47]
	s_add_u32 s46, s44, 0x0
	s_addc_u32 s47, s45, 0
	global_load_dword v210, v42, s[46:47]
	s_add_u32 s46, s44, 0x800
	s_addc_u32 s47, s45, 0
	global_load_dword v211, v42, s[46:47]
	s_add_u32 s46, s44, 0x2000
	s_addc_u32 s47, s45, 0
	global_load_dword v212, v42, s[46:47]
	s_add_u32 s46, s44, 0x2800
	s_addc_u32 s47, s45, 0
	global_load_dword v213, v42, s[46:47]
	s_add_u32 s46, s44, 0x4000
	s_addc_u32 s47, s45, 0
	global_load_dword v220, v42, s[46:47]
	s_add_u32 s46, s44, 0x4800
	s_addc_u32 s47, s45, 0
	global_load_dword v221, v42, s[46:47]
	s_add_u32 s46, s44, 0x6000
	s_addc_u32 s47, s45, 0
	global_load_dword v222, v42, s[46:47]
	s_add_u32 s46, s44, 0x6800
	s_addc_u32 s47, s45, 0
	global_load_dword v223, v42, s[46:47]
	s_add_u32 s46, s44, 0x8000
	s_addc_u32 s47, s45, 0
	global_load_dword v224, v42, s[46:47]
	s_add_u32 s46, s44, 0x8800
	s_addc_u32 s47, s45, 0
	global_load_dword v225, v42, s[46:47]
	s_add_u32 s46, s44, 0xa000
	s_addc_u32 s47, s45, 0
	global_load_dword v226, v42, s[46:47]
	s_add_u32 s46, s44, 0xa800
	s_addc_u32 s47, s45, 0
	global_load_dword v227, v42, s[46:47]
	s_add_u32 s46, s44, 0xc000
	s_addc_u32 s47, s45, 0
	global_load_dword v228, v42, s[46:47]
	s_add_u32 s46, s44, 0xc800
	s_addc_u32 s47, s45, 0
	global_load_dword v229, v42, s[46:47]
	s_add_u32 s46, s44, 0xe000
	s_addc_u32 s47, s45, 0
	global_load_dword v230, v42, s[46:47]
	s_add_u32 s46, s44, 0xe800
	s_addc_u32 s47, s45, 0
	global_load_dword v231, v42, s[46:47]
	s_add_u32 s46, s44, 0x10000
	s_addc_u32 s47, s45, 0
	global_load_dword v232, v42, s[46:47]
	s_add_u32 s46, s44, 0x10800
	s_addc_u32 s47, s45, 0
	global_load_dword v233, v42, s[46:47]
	s_add_u32 s46, s44, 0x12000
	s_addc_u32 s47, s45, 0
	global_load_dword v234, v42, s[46:47]
	s_add_u32 s46, s44, 0x12800
	s_addc_u32 s47, s45, 0
	global_load_dword v235, v42, s[46:47]
	s_add_u32 s46, s44, 0x14000
	s_addc_u32 s47, s45, 0
	global_load_dword v236, v42, s[46:47]
	s_add_u32 s46, s44, 0x14800
	s_addc_u32 s47, s45, 0
	global_load_dword v237, v42, s[46:47]
	s_add_u32 s46, s44, 0x16000
	s_addc_u32 s47, s45, 0
	global_load_dword v238, v42, s[46:47]
	s_add_u32 s46, s44, 0x16800
	s_addc_u32 s47, s45, 0
	global_load_dword v239, v42, s[46:47]
	s_add_u32 s46, s44, 0x18000
	s_addc_u32 s47, s45, 0
	global_load_dword v240, v42, s[46:47]
	s_add_u32 s46, s44, 0x18800
	s_addc_u32 s47, s45, 0
	global_load_dword v241, v42, s[46:47]
	s_add_u32 s46, s44, 0x1a000
	s_addc_u32 s47, s45, 0
	global_load_dword v242, v42, s[46:47]
	s_add_u32 s46, s44, 0x1a800
	s_addc_u32 s47, s45, 0
	global_load_dword v243, v42, s[46:47]
	s_add_u32 s46, s44, 0x1c000
	s_addc_u32 s47, s45, 0
	global_load_dword v244, v42, s[46:47]
	s_add_u32 s46, s44, 0x1c800
	s_addc_u32 s47, s45, 0
	global_load_dword v245, v42, s[46:47]
	s_waitcnt vmcnt(0)
	v_mul_f32_e32 v13, 0xbfb8aa3b, v206
	v_exp_f32_e32 v13, v13
	s_nop 0
	v_add_f32_e32 v13, 1.0, v13
	v_div_scale_f32 v35, s[2:3], v13, v13, v206
	v_rcp_f32_e32 v43, v35
	v_div_scale_f32 v44, vcc, v206, v13, v206
	v_fma_f32 v45, -v35, v43, 1.0
	v_fmac_f32_e32 v43, v45, v43
	v_mul_f32_e32 v45, v44, v43
	v_fma_f32 v46, -v35, v45, v44
	v_fmac_f32_e32 v45, v46, v43
	v_fma_f32 v35, -v35, v45, v44
	v_div_fmas_f32 v35, v35, v43, v45
	v_div_fixup_f32 v12, v35, v13, v206
	ds_write_b32 v34, v12
	v_add_u32_e32 v34, 0x800, v34
	v_mul_f32_e32 v13, 0xbfb8aa3b, v207
	v_exp_f32_e32 v13, v13
	s_nop 0
	v_add_f32_e32 v13, 1.0, v13
	v_div_scale_f32 v35, s[2:3], v13, v13, v207
	v_rcp_f32_e32 v43, v35
	v_div_scale_f32 v44, vcc, v207, v13, v207
	v_fma_f32 v45, -v35, v43, 1.0
	v_fmac_f32_e32 v43, v45, v43
	v_mul_f32_e32 v45, v44, v43
	v_fma_f32 v46, -v35, v45, v44
	v_fmac_f32_e32 v45, v46, v43
	v_fma_f32 v35, -v35, v45, v44
	v_div_fmas_f32 v35, v35, v43, v45
	v_div_fixup_f32 v12, v35, v13, v207
	ds_write_b32 v34, v12
	v_add_u32_e32 v34, 0x800, v34
	v_mul_f32_e32 v13, 0xbfb8aa3b, v208
	v_exp_f32_e32 v13, v13
	s_nop 0
	v_add_f32_e32 v13, 1.0, v13
	v_div_scale_f32 v35, s[2:3], v13, v13, v208
	v_rcp_f32_e32 v43, v35
	v_div_scale_f32 v44, vcc, v208, v13, v208
	v_fma_f32 v45, -v35, v43, 1.0
	v_fmac_f32_e32 v43, v45, v43
	v_mul_f32_e32 v45, v44, v43
	v_fma_f32 v46, -v35, v45, v44
	v_fmac_f32_e32 v45, v46, v43
	v_fma_f32 v35, -v35, v45, v44
	v_div_fmas_f32 v35, v35, v43, v45
	v_div_fixup_f32 v12, v35, v13, v208
	ds_write_b32 v34, v12
	v_add_u32_e32 v34, 0x800, v34
	v_mul_f32_e32 v13, 0xbfb8aa3b, v209
	v_exp_f32_e32 v13, v13
	s_nop 0
	v_add_f32_e32 v13, 1.0, v13
	v_div_scale_f32 v35, s[2:3], v13, v13, v209
	v_rcp_f32_e32 v43, v35
	v_div_scale_f32 v44, vcc, v209, v13, v209
	v_fma_f32 v45, -v35, v43, 1.0
	v_fmac_f32_e32 v43, v45, v43
	v_mul_f32_e32 v45, v44, v43
	v_fma_f32 v46, -v35, v45, v44
	v_fmac_f32_e32 v45, v46, v43
	v_fma_f32 v35, -v35, v45, v44
	v_div_fmas_f32 v35, v35, v43, v45
	v_div_fixup_f32 v12, v35, v13, v209
	ds_write_b32 v34, v12
	v_add_u32_e32 v34, 0x800, v34
	v_mul_f32_e32 v13, 0xbfb8aa3b, v210
	v_exp_f32_e32 v13, v13
	s_nop 0
	v_add_f32_e32 v13, 1.0, v13
	v_div_scale_f32 v35, s[2:3], v13, v13, v210
; __device__ __forceinline__ void phase0(CArgs a, LAS unsigned char* lds, int tid, int lane, int wave, int G, int bx) {
;     ...
;             for (int idx = tid; idx < NB * 1024; idx += 512) { const int r = idx >> 10, k = idx & 1023;
;                 const float c = r < 2 ? a->in[7][r * D + half * 1024 + k] : a->in[8][(r - 2) * D + half * 1024 + k];
;                 S[idx] = c / (1.0f + __expf(-c)); }
	v_rcp_f32_e32 v43, v35
	v_div_scale_f32 v44, vcc, v210, v13, v210
	v_fma_f32 v45, -v35, v43, 1.0
	v_fmac_f32_e32 v43, v45, v43
	v_mul_f32_e32 v45, v44, v43
	v_fma_f32 v46, -v35, v45, v44
	v_fmac_f32_e32 v45, v46, v43
	v_fma_f32 v35, -v35, v45, v44
	v_div_fmas_f32 v35, v35, v43, v45
	v_div_fixup_f32 v12, v35, v13, v210
	ds_write_b32 v34, v12
	v_add_u32_e32 v34, 0x800, v34
	v_mul_f32_e32 v13, 0xbfb8aa3b, v211
	v_exp_f32_e32 v13, v13
	s_nop 0
	v_add_f32_e32 v13, 1.0, v13
	v_div_scale_f32 v35, s[2:3], v13, v13, v211
	v_rcp_f32_e32 v43, v35
	v_div_scale_f32 v44, vcc, v211, v13, v211
	v_fma_f32 v45, -v35, v43, 1.0
	v_fmac_f32_e32 v43, v45, v43
	v_mul_f32_e32 v45, v44, v43
	v_fma_f32 v46, -v35, v45, v44
	v_fmac_f32_e32 v45, v46, v43
	v_fma_f32 v35, -v35, v45, v44
	v_div_fmas_f32 v35, v35, v43, v45
	v_div_fixup_f32 v12, v35, v13, v211
	ds_write_b32 v34, v12
	v_add_u32_e32 v34, 0x800, v34
	v_mul_f32_e32 v13, 0xbfb8aa3b, v212
	v_exp_f32_e32 v13, v13
	s_nop 0
	v_add_f32_e32 v13, 1.0, v13
	v_div_scale_f32 v35, s[2:3], v13, v13, v212
	v_rcp_f32_e32 v43, v35
	v_div_scale_f32 v44, vcc, v212, v13, v212
	v_fma_f32 v45, -v35, v43, 1.0
	v_fmac_f32_e32 v43, v45, v43
	v_mul_f32_e32 v45, v44, v43
	v_fma_f32 v46, -v35, v45, v44
	v_fmac_f32_e32 v45, v46, v43
	v_fma_f32 v35, -v35, v45, v44
	v_div_fmas_f32 v35, v35, v43, v45
	v_div_fixup_f32 v12, v35, v13, v212
	ds_write_b32 v34, v12
	v_add_u32_e32 v34, 0x800, v34
	v_mul_f32_e32 v13, 0xbfb8aa3b, v213
	v_exp_f32_e32 v13, v13
	s_nop 0
	v_add_f32_e32 v13, 1.0, v13
	v_div_scale_f32 v35, s[2:3], v13, v13, v213
	v_rcp_f32_e32 v43, v35
	v_div_scale_f32 v44, vcc, v213, v13, v213
	v_fma_f32 v45, -v35, v43, 1.0
	v_fmac_f32_e32 v43, v45, v43
	v_mul_f32_e32 v45, v44, v43
	v_fma_f32 v46, -v35, v45, v44
	v_fmac_f32_e32 v45, v46, v43
	v_fma_f32 v35, -v35, v45, v44
	v_div_fmas_f32 v35, v35, v43, v45
	v_div_fixup_f32 v12, v35, v13, v213
	ds_write_b32 v34, v12
	v_add_u32_e32 v34, 0x800, v34
	v_mul_f32_e32 v13, 0xbfb8aa3b, v220
	v_exp_f32_e32 v13, v13
	s_nop 0
	v_add_f32_e32 v13, 1.0, v13
	v_div_scale_f32 v35, s[2:3], v13, v13, v220
	v_rcp_f32_e32 v43, v35
	v_div_scale_f32 v44, vcc, v220, v13, v220
	v_fma_f32 v45, -v35, v43, 1.0
	v_fmac_f32_e32 v43, v45, v43
	v_mul_f32_e32 v45, v44, v43
	v_fma_f32 v46, -v35, v45, v44
	v_fmac_f32_e32 v45, v46, v43
	v_fma_f32 v35, -v35, v45, v44
	v_div_fmas_f32 v35, v35, v43, v45
	v_div_fixup_f32 v12, v35, v13, v220
	ds_write_b32 v34, v12
	v_add_u32_e32 v34, 0x800, v34
	v_mul_f32_e32 v13, 0xbfb8aa3b, v221
	v_exp_f32_e32 v13, v13
	s_nop 0
	v_add_f32_e32 v13, 1.0, v13
	v_div_scale_f32 v35, s[2:3], v13, v13, v221
	v_rcp_f32_e32 v43, v35
	v_div_scale_f32 v44, vcc, v221, v13, v221
	v_fma_f32 v45, -v35, v43, 1.0
	v_fmac_f32_e32 v43, v45, v43
	v_mul_f32_e32 v45, v44, v43
	v_fma_f32 v46, -v35, v45, v44
	v_fmac_f32_e32 v45, v46, v43
	v_fma_f32 v35, -v35, v45, v44
	v_div_fmas_f32 v35, v35, v43, v45
	v_div_fixup_f32 v12, v35, v13, v221
	ds_write_b32 v34, v12
	v_add_u32_e32 v34, 0x800, v34
	v_mul_f32_e32 v13, 0xbfb8aa3b, v222
	v_exp_f32_e32 v13, v13
	s_nop 0
	v_add_f32_e32 v13, 1.0, v13
	v_div_scale_f32 v35, s[2:3], v13, v13, v222
	v_rcp_f32_e32 v43, v35
	v_div_scale_f32 v44, vcc, v222, v13, v222
	v_fma_f32 v45, -v35, v43, 1.0
	v_fmac_f32_e32 v43, v45, v43
	v_mul_f32_e32 v45, v44, v43
	v_fma_f32 v46, -v35, v45, v44
	v_fmac_f32_e32 v45, v46, v43
	v_fma_f32 v35, -v35, v45, v44
	v_div_fmas_f32 v35, v35, v43, v45
	v_div_fixup_f32 v12, v35, v13, v222
	ds_write_b32 v34, v12
	v_add_u32_e32 v34, 0x800, v34
	v_mul_f32_e32 v13, 0xbfb8aa3b, v223
	v_exp_f32_e32 v13, v13
	s_nop 0
	v_add_f32_e32 v13, 1.0, v13
	v_div_scale_f32 v35, s[2:3], v13, v13, v223
	v_rcp_f32_e32 v43, v35
	v_div_scale_f32 v44, vcc, v223, v13, v223
	v_fma_f32 v45, -v35, v43, 1.0
	v_fmac_f32_e32 v43, v45, v43
	v_mul_f32_e32 v45, v44, v43
	v_fma_f32 v46, -v35, v45, v44
	v_fmac_f32_e32 v45, v46, v43
	v_fma_f32 v35, -v35, v45, v44
	v_div_fmas_f32 v35, v35, v43, v45
	v_div_fixup_f32 v12, v35, v13, v223
	ds_write_b32 v34, v12
	v_add_u32_e32 v34, 0x800, v34
	v_mul_f32_e32 v13, 0xbfb8aa3b, v224
	v_exp_f32_e32 v13, v13
	s_nop 0
	v_add_f32_e32 v13, 1.0, v13
	v_div_scale_f32 v35, s[2:3], v13, v13, v224
	v_rcp_f32_e32 v43, v35
	v_div_scale_f32 v44, vcc, v224, v13, v224
	v_fma_f32 v45, -v35, v43, 1.0
	v_fmac_f32_e32 v43, v45, v43
	v_mul_f32_e32 v45, v44, v43
	v_fma_f32 v46, -v35, v45, v44
	v_fmac_f32_e32 v45, v46, v43
	v_fma_f32 v35, -v35, v45, v44
	v_div_fmas_f32 v35, v35, v43, v45
	v_div_fixup_f32 v12, v35, v13, v224
	ds_write_b32 v34, v12
	v_add_u32_e32 v34, 0x800, v34
	v_mul_f32_e32 v13, 0xbfb8aa3b, v225
	v_exp_f32_e32 v13, v13
	s_nop 0
	v_add_f32_e32 v13, 1.0, v13
	v_div_scale_f32 v35, s[2:3], v13, v13, v225
	v_rcp_f32_e32 v43, v35
	v_div_scale_f32 v44, vcc, v225, v13, v225
	v_fma_f32 v45, -v35, v43, 1.0
	v_fmac_f32_e32 v43, v45, v43
	v_mul_f32_e32 v45, v44, v43
	v_fma_f32 v46, -v35, v45, v44
	v_fmac_f32_e32 v45, v46, v43
	v_fma_f32 v35, -v35, v45, v44
	v_div_fmas_f32 v35, v35, v43, v45
	v_div_fixup_f32 v12, v35, v13, v225
	ds_write_b32 v34, v12
	v_add_u32_e32 v34, 0x800, v34
	v_mul_f32_e32 v13, 0xbfb8aa3b, v226
	v_exp_f32_e32 v13, v13
	s_nop 0
	v_add_f32_e32 v13, 1.0, v13
	v_div_scale_f32 v35, s[2:3], v13, v13, v226
	v_rcp_f32_e32 v43, v35
	v_div_scale_f32 v44, vcc, v226, v13, v226
	v_fma_f32 v45, -v35, v43, 1.0
	v_fmac_f32_e32 v43, v45, v43
	v_mul_f32_e32 v45, v44, v43
	v_fma_f32 v46, -v35, v45, v44
	v_fmac_f32_e32 v45, v46, v43
	v_fma_f32 v35, -v35, v45, v44
	v_div_fmas_f32 v35, v35, v43, v45
	v_div_fixup_f32 v12, v35, v13, v226
	ds_write_b32 v34, v12
	v_add_u32_e32 v34, 0x800, v34
	v_mul_f32_e32 v13, 0xbfb8aa3b, v227
	v_exp_f32_e32 v13, v13
	s_nop 0
; __device__ __forceinline__ void phase0(CArgs a, LAS unsigned char* lds, int tid, int lane, int wave, int G, int bx) {
;     ...
;             for (int idx = tid; idx < NB * 1024; idx += 512) { const int r = idx >> 10, k = idx & 1023;
;                 const float c = r < 2 ? a->in[7][r * D + half * 1024 + k] : a->in[8][(r - 2) * D + half * 1024 + k];
;                 S[idx] = c / (1.0f + __expf(-c)); }
	v_add_f32_e32 v13, 1.0, v13
	v_div_scale_f32 v35, s[2:3], v13, v13, v227
	v_rcp_f32_e32 v43, v35
	v_div_scale_f32 v44, vcc, v227, v13, v227
	v_fma_f32 v45, -v35, v43, 1.0
	v_fmac_f32_e32 v43, v45, v43
	v_mul_f32_e32 v45, v44, v43
	v_fma_f32 v46, -v35, v45, v44
	v_fmac_f32_e32 v45, v46, v43
	v_fma_f32 v35, -v35, v45, v44
	v_div_fmas_f32 v35, v35, v43, v45
	v_div_fixup_f32 v12, v35, v13, v227
	ds_write_b32 v34, v12
	v_add_u32_e32 v34, 0x800, v34
	v_mul_f32_e32 v13, 0xbfb8aa3b, v228
	v_exp_f32_e32 v13, v13
	s_nop 0
	v_add_f32_e32 v13, 1.0, v13
	v_div_scale_f32 v35, s[2:3], v13, v13, v228
	v_rcp_f32_e32 v43, v35
	v_div_scale_f32 v44, vcc, v228, v13, v228
	v_fma_f32 v45, -v35, v43, 1.0
	v_fmac_f32_e32 v43, v45, v43
	v_mul_f32_e32 v45, v44, v43
	v_fma_f32 v46, -v35, v45, v44
	v_fmac_f32_e32 v45, v46, v43
	v_fma_f32 v35, -v35, v45, v44
	v_div_fmas_f32 v35, v35, v43, v45
	v_div_fixup_f32 v12, v35, v13, v228
	ds_write_b32 v34, v12
	v_add_u32_e32 v34, 0x800, v34
	v_mul_f32_e32 v13, 0xbfb8aa3b, v229
	v_exp_f32_e32 v13, v13
	s_nop 0
	v_add_f32_e32 v13, 1.0, v13
	v_div_scale_f32 v35, s[2:3], v13, v13, v229
	v_rcp_f32_e32 v43, v35
	v_div_scale_f32 v44, vcc, v229, v13, v229
	v_fma_f32 v45, -v35, v43, 1.0
	v_fmac_f32_e32 v43, v45, v43
	v_mul_f32_e32 v45, v44, v43
	v_fma_f32 v46, -v35, v45, v44
	v_fmac_f32_e32 v45, v46, v43
	v_fma_f32 v35, -v35, v45, v44
	v_div_fmas_f32 v35, v35, v43, v45
	v_div_fixup_f32 v12, v35, v13, v229
	ds_write_b32 v34, v12
	v_add_u32_e32 v34, 0x800, v34
	v_mul_f32_e32 v13, 0xbfb8aa3b, v230
	v_exp_f32_e32 v13, v13
	s_nop 0
	v_add_f32_e32 v13, 1.0, v13
	v_div_scale_f32 v35, s[2:3], v13, v13, v230
	v_rcp_f32_e32 v43, v35
	v_div_scale_f32 v44, vcc, v230, v13, v230
	v_fma_f32 v45, -v35, v43, 1.0
	v_fmac_f32_e32 v43, v45, v43
	v_mul_f32_e32 v45, v44, v43
	v_fma_f32 v46, -v35, v45, v44
	v_fmac_f32_e32 v45, v46, v43
	v_fma_f32 v35, -v35, v45, v44
	v_div_fmas_f32 v35, v35, v43, v45
	v_div_fixup_f32 v12, v35, v13, v230
	ds_write_b32 v34, v12
	v_add_u32_e32 v34, 0x800, v34
	v_mul_f32_e32 v13, 0xbfb8aa3b, v231
	v_exp_f32_e32 v13, v13
	s_nop 0
	v_add_f32_e32 v13, 1.0, v13
	v_div_scale_f32 v35, s[2:3], v13, v13, v231
	v_rcp_f32_e32 v43, v35
	v_div_scale_f32 v44, vcc, v231, v13, v231
	v_fma_f32 v45, -v35, v43, 1.0
	v_fmac_f32_e32 v43, v45, v43
	v_mul_f32_e32 v45, v44, v43
	v_fma_f32 v46, -v35, v45, v44
	v_fmac_f32_e32 v45, v46, v43
	v_fma_f32 v35, -v35, v45, v44
	v_div_fmas_f32 v35, v35, v43, v45
	v_div_fixup_f32 v12, v35, v13, v231
	ds_write_b32 v34, v12
	v_add_u32_e32 v34, 0x800, v34
	v_mul_f32_e32 v13, 0xbfb8aa3b, v232
	v_exp_f32_e32 v13, v13
	s_nop 0
	v_add_f32_e32 v13, 1.0, v13
	v_div_scale_f32 v35, s[2:3], v13, v13, v232
	v_rcp_f32_e32 v43, v35
	v_div_scale_f32 v44, vcc, v232, v13, v232
	v_fma_f32 v45, -v35, v43, 1.0
	v_fmac_f32_e32 v43, v45, v43
	v_mul_f32_e32 v45, v44, v43
	v_fma_f32 v46, -v35, v45, v44
	v_fmac_f32_e32 v45, v46, v43
	v_fma_f32 v35, -v35, v45, v44
	v_div_fmas_f32 v35, v35, v43, v45
	v_div_fixup_f32 v12, v35, v13, v232
	ds_write_b32 v34, v12
	v_add_u32_e32 v34, 0x800, v34
	v_mul_f32_e32 v13, 0xbfb8aa3b, v233
	v_exp_f32_e32 v13, v13
	s_nop 0
	v_add_f32_e32 v13, 1.0, v13
	v_div_scale_f32 v35, s[2:3], v13, v13, v233
	v_rcp_f32_e32 v43, v35
	v_div_scale_f32 v44, vcc, v233, v13, v233
	v_fma_f32 v45, -v35, v43, 1.0
	v_fmac_f32_e32 v43, v45, v43
	v_mul_f32_e32 v45, v44, v43
	v_fma_f32 v46, -v35, v45, v44
	v_fmac_f32_e32 v45, v46, v43
	v_fma_f32 v35, -v35, v45, v44
	v_div_fmas_f32 v35, v35, v43, v45
	v_div_fixup_f32 v12, v35, v13, v233
	ds_write_b32 v34, v12
	v_add_u32_e32 v34, 0x800, v34
	v_mul_f32_e32 v13, 0xbfb8aa3b, v234
	v_exp_f32_e32 v13, v13
	s_nop 0
	v_add_f32_e32 v13, 1.0, v13
	v_div_scale_f32 v35, s[2:3], v13, v13, v234
	v_rcp_f32_e32 v43, v35
	v_div_scale_f32 v44, vcc, v234, v13, v234
	v_fma_f32 v45, -v35, v43, 1.0
	v_fmac_f32_e32 v43, v45, v43
	v_mul_f32_e32 v45, v44, v43
	v_fma_f32 v46, -v35, v45, v44
	v_fmac_f32_e32 v45, v46, v43
	v_fma_f32 v35, -v35, v45, v44
	v_div_fmas_f32 v35, v35, v43, v45
	v_div_fixup_f32 v12, v35, v13, v234
	ds_write_b32 v34, v12
	v_add_u32_e32 v34, 0x800, v34
	v_mul_f32_e32 v13, 0xbfb8aa3b, v235
	v_exp_f32_e32 v13, v13
	s_nop 0
	v_add_f32_e32 v13, 1.0, v13
	v_div_scale_f32 v35, s[2:3], v13, v13, v235
	v_rcp_f32_e32 v43, v35
	v_div_scale_f32 v44, vcc, v235, v13, v235
	v_fma_f32 v45, -v35, v43, 1.0
	v_fmac_f32_e32 v43, v45, v43
	v_mul_f32_e32 v45, v44, v43
	v_fma_f32 v46, -v35, v45, v44
	v_fmac_f32_e32 v45, v46, v43
	v_fma_f32 v35, -v35, v45, v44
	v_div_fmas_f32 v35, v35, v43, v45
	v_div_fixup_f32 v12, v35, v13, v235
	ds_write_b32 v34, v12
	v_add_u32_e32 v34, 0x800, v34
	v_mul_f32_e32 v13, 0xbfb8aa3b, v236
	v_exp_f32_e32 v13, v13
	s_nop 0
	v_add_f32_e32 v13, 1.0, v13
	v_div_scale_f32 v35, s[2:3], v13, v13, v236
	v_rcp_f32_e32 v43, v35
	v_div_scale_f32 v44, vcc, v236, v13, v236
	v_fma_f32 v45, -v35, v43, 1.0
	v_fmac_f32_e32 v43, v45, v43
	v_mul_f32_e32 v45, v44, v43
	v_fma_f32 v46, -v35, v45, v44
	v_fmac_f32_e32 v45, v46, v43
	v_fma_f32 v35, -v35, v45, v44
	v_div_fmas_f32 v35, v35, v43, v45
	v_div_fixup_f32 v12, v35, v13, v236
	ds_write_b32 v34, v12
	v_add_u32_e32 v34, 0x800, v34
	v_mul_f32_e32 v13, 0xbfb8aa3b, v237
	v_exp_f32_e32 v13, v13
	s_nop 0
	v_add_f32_e32 v13, 1.0, v13
	v_div_scale_f32 v35, s[2:3], v13, v13, v237
	v_rcp_f32_e32 v43, v35
	v_div_scale_f32 v44, vcc, v237, v13, v237
	v_fma_f32 v45, -v35, v43, 1.0
	v_fmac_f32_e32 v43, v45, v43
	v_mul_f32_e32 v45, v44, v43
	v_fma_f32 v46, -v35, v45, v44
	v_fmac_f32_e32 v45, v46, v43
	v_fma_f32 v35, -v35, v45, v44
	v_div_fmas_f32 v35, v35, v43, v45
	v_div_fixup_f32 v12, v35, v13, v237
	ds_write_b32 v34, v12
	v_add_u32_e32 v34, 0x800, v34
; __device__ __forceinline__ void phase0(CArgs a, LAS unsigned char* lds, int tid, int lane, int wave, int G, int bx) {
;     ...
;             for (int idx = tid; idx < NB * 1024; idx += 512) { const int r = idx >> 10, k = idx & 1023;
;                 const float c = r < 2 ? a->in[7][r * D + half * 1024 + k] : a->in[8][(r - 2) * D + half * 1024 + k];
;                 S[idx] = c / (1.0f + __expf(-c)); }
	v_mul_f32_e32 v13, 0xbfb8aa3b, v238
	v_exp_f32_e32 v13, v13
	s_nop 0
	v_add_f32_e32 v13, 1.0, v13
	v_div_scale_f32 v35, s[2:3], v13, v13, v238
	v_rcp_f32_e32 v43, v35
	v_div_scale_f32 v44, vcc, v238, v13, v238
	v_fma_f32 v45, -v35, v43, 1.0
	v_fmac_f32_e32 v43, v45, v43
	v_mul_f32_e32 v45, v44, v43
	v_fma_f32 v46, -v35, v45, v44
	v_fmac_f32_e32 v45, v46, v43
	v_fma_f32 v35, -v35, v45, v44
	v_div_fmas_f32 v35, v35, v43, v45
	v_div_fixup_f32 v12, v35, v13, v238
	ds_write_b32 v34, v12
	v_add_u32_e32 v34, 0x800, v34
	v_mul_f32_e32 v13, 0xbfb8aa3b, v239
	v_exp_f32_e32 v13, v13
	s_nop 0
	v_add_f32_e32 v13, 1.0, v13
	v_div_scale_f32 v35, s[2:3], v13, v13, v239
	v_rcp_f32_e32 v43, v35
	v_div_scale_f32 v44, vcc, v239, v13, v239
	v_fma_f32 v45, -v35, v43, 1.0
	v_fmac_f32_e32 v43, v45, v43
	v_mul_f32_e32 v45, v44, v43
	v_fma_f32 v46, -v35, v45, v44
	v_fmac_f32_e32 v45, v46, v43
	v_fma_f32 v35, -v35, v45, v44
	v_div_fmas_f32 v35, v35, v43, v45
	v_div_fixup_f32 v12, v35, v13, v239
	ds_write_b32 v34, v12
	v_add_u32_e32 v34, 0x800, v34
	v_mul_f32_e32 v13, 0xbfb8aa3b, v240
	v_exp_f32_e32 v13, v13
	s_nop 0
	v_add_f32_e32 v13, 1.0, v13
	v_div_scale_f32 v35, s[2:3], v13, v13, v240
	v_rcp_f32_e32 v43, v35
	v_div_scale_f32 v44, vcc, v240, v13, v240
	v_fma_f32 v45, -v35, v43, 1.0
	v_fmac_f32_e32 v43, v45, v43
	v_mul_f32_e32 v45, v44, v43
	v_fma_f32 v46, -v35, v45, v44
	v_fmac_f32_e32 v45, v46, v43
	v_fma_f32 v35, -v35, v45, v44
	v_div_fmas_f32 v35, v35, v43, v45
	v_div_fixup_f32 v12, v35, v13, v240
	ds_write_b32 v34, v12
	v_add_u32_e32 v34, 0x800, v34
	v_mul_f32_e32 v13, 0xbfb8aa3b, v241
	v_exp_f32_e32 v13, v13
	s_nop 0
	v_add_f32_e32 v13, 1.0, v13
	v_div_scale_f32 v35, s[2:3], v13, v13, v241
	v_rcp_f32_e32 v43, v35
	v_div_scale_f32 v44, vcc, v241, v13, v241
	v_fma_f32 v45, -v35, v43, 1.0
	v_fmac_f32_e32 v43, v45, v43
	v_mul_f32_e32 v45, v44, v43
	v_fma_f32 v46, -v35, v45, v44
	v_fmac_f32_e32 v45, v46, v43
	v_fma_f32 v35, -v35, v45, v44
	v_div_fmas_f32 v35, v35, v43, v45
	v_div_fixup_f32 v12, v35, v13, v241
	ds_write_b32 v34, v12
	v_add_u32_e32 v34, 0x800, v34
	v_mul_f32_e32 v13, 0xbfb8aa3b, v242
	v_exp_f32_e32 v13, v13
	s_nop 0
	v_add_f32_e32 v13, 1.0, v13
	v_div_scale_f32 v35, s[2:3], v13, v13, v242
	v_rcp_f32_e32 v43, v35
	v_div_scale_f32 v44, vcc, v242, v13, v242
	v_fma_f32 v45, -v35, v43, 1.0
	v_fmac_f32_e32 v43, v45, v43
	v_mul_f32_e32 v45, v44, v43
	v_fma_f32 v46, -v35, v45, v44
	v_fmac_f32_e32 v45, v46, v43
	v_fma_f32 v35, -v35, v45, v44
	v_div_fmas_f32 v35, v35, v43, v45
	v_div_fixup_f32 v12, v35, v13, v242
	ds_write_b32 v34, v12
	v_add_u32_e32 v34, 0x800, v34
	v_mul_f32_e32 v13, 0xbfb8aa3b, v243
	v_exp_f32_e32 v13, v13
	s_nop 0
	v_add_f32_e32 v13, 1.0, v13
	v_div_scale_f32 v35, s[2:3], v13, v13, v243
	v_rcp_f32_e32 v43, v35
	v_div_scale_f32 v44, vcc, v243, v13, v243
	v_fma_f32 v45, -v35, v43, 1.0
	v_fmac_f32_e32 v43, v45, v43
	v_mul_f32_e32 v45, v44, v43
	v_fma_f32 v46, -v35, v45, v44
	v_fmac_f32_e32 v45, v46, v43
	v_fma_f32 v35, -v35, v45, v44
	v_div_fmas_f32 v35, v35, v43, v45
	v_div_fixup_f32 v12, v35, v13, v243
	ds_write_b32 v34, v12
	v_add_u32_e32 v34, 0x800, v34
	v_mul_f32_e32 v13, 0xbfb8aa3b, v244
	v_exp_f32_e32 v13, v13
	s_nop 0
	v_add_f32_e32 v13, 1.0, v13
	v_div_scale_f32 v35, s[2:3], v13, v13, v244
	v_rcp_f32_e32 v43, v35
	v_div_scale_f32 v44, vcc, v244, v13, v244
	v_fma_f32 v45, -v35, v43, 1.0
	v_fmac_f32_e32 v43, v45, v43
	v_mul_f32_e32 v45, v44, v43
	v_fma_f32 v46, -v35, v45, v44
	v_fmac_f32_e32 v45, v46, v43
	v_fma_f32 v35, -v35, v45, v44
	v_div_fmas_f32 v35, v35, v43, v45
	v_div_fixup_f32 v12, v35, v13, v244
	ds_write_b32 v34, v12
	v_add_u32_e32 v34, 0x800, v34
	v_mul_f32_e32 v13, 0xbfb8aa3b, v245
	v_exp_f32_e32 v13, v13
	s_nop 0
	v_add_f32_e32 v13, 1.0, v13
	v_div_scale_f32 v35, s[2:3], v13, v13, v245
	v_rcp_f32_e32 v43, v35
	v_div_scale_f32 v44, vcc, v245, v13, v245
	v_fma_f32 v45, -v35, v43, 1.0
	v_fmac_f32_e32 v43, v45, v43
	v_mul_f32_e32 v45, v44, v43
	v_fma_f32 v46, -v35, v45, v44
	v_fmac_f32_e32 v45, v46, v43
	v_fma_f32 v35, -v35, v45, v44
	v_div_fmas_f32 v35, v35, v43, v45
	v_div_fixup_f32 v12, v35, v13, v245
	ds_write_b32 v34, v12
	v_add_u32_e32 v34, 0x800, v34
	s_add_u32 s46, s44, 0x1e000
	s_addc_u32 s47, s45, 0
	global_load_dword v206, v42, s[46:47]
	s_add_u32 s46, s44, 0x1e800
	s_addc_u32 s47, s45, 0
	global_load_dword v207, v42, s[46:47]
	s_add_u32 s46, s44, 0x20000
	s_addc_u32 s47, s45, 0
	global_load_dword v208, v42, s[46:47]
	s_add_u32 s46, s44, 0x20800
	s_addc_u32 s47, s45, 0
	global_load_dword v209, v42, s[46:47]
	s_add_u32 s46, s44, 0x22000
	s_addc_u32 s47, s45, 0
	global_load_dword v210, v42, s[46:47]
	s_add_u32 s46, s44, 0x22800
	s_addc_u32 s47, s45, 0
	global_load_dword v211, v42, s[46:47]
	s_add_u32 s46, s44, 0x24000
	s_addc_u32 s47, s45, 0
	global_load_dword v212, v42, s[46:47]
	s_add_u32 s46, s44, 0x24800
	s_addc_u32 s47, s45, 0
	global_load_dword v213, v42, s[46:47]
	s_add_u32 s46, s44, 0x26000
	s_addc_u32 s47, s45, 0
	global_load_dword v220, v42, s[46:47]
	s_add_u32 s46, s44, 0x26800
	s_addc_u32 s47, s45, 0
	global_load_dword v221, v42, s[46:47]
	s_add_u32 s46, s44, 0x28000
	s_addc_u32 s47, s45, 0
	global_load_dword v222, v42, s[46:47]
	s_add_u32 s46, s44, 0x28800
	s_addc_u32 s47, s45, 0
	global_load_dword v223, v42, s[46:47]
	s_add_u32 s46, s44, 0x2a000
	s_addc_u32 s47, s45, 0
	global_load_dword v224, v42, s[46:47]
	s_add_u32 s46, s44, 0x2a800
	s_addc_u32 s47, s45, 0
	global_load_dword v225, v42, s[46:47]
	s_add_u32 s46, s44, 0x2c000
	s_addc_u32 s47, s45, 0
	global_load_dword v226, v42, s[46:47]
	s_add_u32 s46, s44, 0x2c800
	s_addc_u32 s47, s45, 0
	global_load_dword v227, v42, s[46:47]
	s_add_u32 s46, s44, 0x2e000
; __device__ __forceinline__ void phase0(CArgs a, LAS unsigned char* lds, int tid, int lane, int wave, int G, int bx) {
;     ...
;             for (int idx = tid; idx < NB * 1024; idx += 512) { const int r = idx >> 10, k = idx & 1023;
;                 const float c = r < 2 ? a->in[7][r * D + half * 1024 + k] : a->in[8][(r - 2) * D + half * 1024 + k];
;                 S[idx] = c / (1.0f + __expf(-c)); }
	s_addc_u32 s47, s45, 0
	global_load_dword v228, v42, s[46:47]
	s_add_u32 s46, s44, 0x2e800
	s_addc_u32 s47, s45, 0
	global_load_dword v229, v42, s[46:47]
	s_add_u32 s46, s44, 0x30000
	s_addc_u32 s47, s45, 0
	global_load_dword v230, v42, s[46:47]
	s_add_u32 s46, s44, 0x30800
	s_addc_u32 s47, s45, 0
	global_load_dword v231, v42, s[46:47]
	s_add_u32 s46, s44, 0x32000
	s_addc_u32 s47, s45, 0
	global_load_dword v232, v42, s[46:47]
	s_add_u32 s46, s44, 0x32800
	s_addc_u32 s47, s45, 0
	global_load_dword v233, v42, s[46:47]
	s_add_u32 s46, s44, 0x34000
	s_addc_u32 s47, s45, 0
	global_load_dword v234, v42, s[46:47]
	s_add_u32 s46, s44, 0x34800
	s_addc_u32 s47, s45, 0
	global_load_dword v235, v42, s[46:47]
	s_add_u32 s46, s44, 0x36000
	s_addc_u32 s47, s45, 0
	global_load_dword v236, v42, s[46:47]
	s_add_u32 s46, s44, 0x36800
	s_addc_u32 s47, s45, 0
	global_load_dword v237, v42, s[46:47]
	s_add_u32 s46, s44, 0x38000
	s_addc_u32 s47, s45, 0
	global_load_dword v238, v42, s[46:47]
	s_add_u32 s46, s44, 0x38800
	s_addc_u32 s47, s45, 0
	global_load_dword v239, v42, s[46:47]
	s_add_u32 s46, s44, 0x3a000
	s_addc_u32 s47, s45, 0
	global_load_dword v240, v42, s[46:47]
	s_add_u32 s46, s44, 0x3a800
	s_addc_u32 s47, s45, 0
	global_load_dword v241, v42, s[46:47]
	s_add_u32 s46, s44, 0x3c000
	s_addc_u32 s47, s45, 0
	global_load_dword v242, v42, s[46:47]
	s_add_u32 s46, s44, 0x3c800
	s_addc_u32 s47, s45, 0
	global_load_dword v243, v42, s[46:47]
	s_add_u32 s46, s44, 0x3e000
	s_addc_u32 s47, s45, 0
	global_load_dword v244, v42, s[46:47]
	s_add_u32 s46, s44, 0x3e800
	s_addc_u32 s47, s45, 0
	global_load_dword v245, v42, s[46:47]
	s_waitcnt vmcnt(0)
	v_mul_f32_e32 v13, 0xbfb8aa3b, v206
	v_exp_f32_e32 v13, v13
	s_nop 0
	v_add_f32_e32 v13, 1.0, v13
	v_div_scale_f32 v35, s[2:3], v13, v13, v206
	v_rcp_f32_e32 v43, v35
	v_div_scale_f32 v44, vcc, v206, v13, v206
	v_fma_f32 v45, -v35, v43, 1.0
	v_fmac_f32_e32 v43, v45, v43
	v_mul_f32_e32 v45, v44, v43
	v_fma_f32 v46, -v35, v45, v44
	v_fmac_f32_e32 v45, v46, v43
	v_fma_f32 v35, -v35, v45, v44
	v_div_fmas_f32 v35, v35, v43, v45
	v_div_fixup_f32 v12, v35, v13, v206
	ds_write_b32 v34, v12
	v_add_u32_e32 v34, 0x800, v34
	v_mul_f32_e32 v13, 0xbfb8aa3b, v207
	v_exp_f32_e32 v13, v13
	s_nop 0
	v_add_f32_e32 v13, 1.0, v13
	v_div_scale_f32 v35, s[2:3], v13, v13, v207
	v_rcp_f32_e32 v43, v35
	v_div_scale_f32 v44, vcc, v207, v13, v207
	v_fma_f32 v45, -v35, v43, 1.0
	v_fmac_f32_e32 v43, v45, v43
	v_mul_f32_e32 v45, v44, v43
	v_fma_f32 v46, -v35, v45, v44
	v_fmac_f32_e32 v45, v46, v43
	v_fma_f32 v35, -v35, v45, v44
	v_div_fmas_f32 v35, v35, v43, v45
	v_div_fixup_f32 v12, v35, v13, v207
	ds_write_b32 v34, v12
	v_add_u32_e32 v34, 0x800, v34
	v_mul_f32_e32 v13, 0xbfb8aa3b, v208
	v_exp_f32_e32 v13, v13
	s_nop 0
	v_add_f32_e32 v13, 1.0, v13
	v_div_scale_f32 v35, s[2:3], v13, v13, v208
	v_rcp_f32_e32 v43, v35
	v_div_scale_f32 v44, vcc, v208, v13, v208
	v_fma_f32 v45, -v35, v43, 1.0
	v_fmac_f32_e32 v43, v45, v43
	v_mul_f32_e32 v45, v44, v43
	v_fma_f32 v46, -v35, v45, v44
	v_fmac_f32_e32 v45, v46, v43
	v_fma_f32 v35, -v35, v45, v44
	v_div_fmas_f32 v35, v35, v43, v45
	v_div_fixup_f32 v12, v35, v13, v208
	ds_write_b32 v34, v12
	v_add_u32_e32 v34, 0x800, v34
	v_mul_f32_e32 v13, 0xbfb8aa3b, v209
	v_exp_f32_e32 v13, v13
	s_nop 0
	v_add_f32_e32 v13, 1.0, v13
	v_div_scale_f32 v35, s[2:3], v13, v13, v209
	v_rcp_f32_e32 v43, v35
	v_div_scale_f32 v44, vcc, v209, v13, v209
	v_fma_f32 v45, -v35, v43, 1.0
	v_fmac_f32_e32 v43, v45, v43
	v_mul_f32_e32 v45, v44, v43
	v_fma_f32 v46, -v35, v45, v44
	v_fmac_f32_e32 v45, v46, v43
	v_fma_f32 v35, -v35, v45, v44
	v_div_fmas_f32 v35, v35, v43, v45
	v_div_fixup_f32 v12, v35, v13, v209
	ds_write_b32 v34, v12
	v_add_u32_e32 v34, 0x800, v34
	v_mul_f32_e32 v13, 0xbfb8aa3b, v210
	v_exp_f32_e32 v13, v13
	s_nop 0
	v_add_f32_e32 v13, 1.0, v13
	v_div_scale_f32 v35, s[2:3], v13, v13, v210
	v_rcp_f32_e32 v43, v35
	v_div_scale_f32 v44, vcc, v210, v13, v210
	v_fma_f32 v45, -v35, v43, 1.0
	v_fmac_f32_e32 v43, v45, v43
	v_mul_f32_e32 v45, v44, v43
	v_fma_f32 v46, -v35, v45, v44
	v_fmac_f32_e32 v45, v46, v43
	v_fma_f32 v35, -v35, v45, v44
	v_div_fmas_f32 v35, v35, v43, v45
	v_div_fixup_f32 v12, v35, v13, v210
	ds_write_b32 v34, v12
	v_add_u32_e32 v34, 0x800, v34
	v_mul_f32_e32 v13, 0xbfb8aa3b, v211
	v_exp_f32_e32 v13, v13
	s_nop 0
	v_add_f32_e32 v13, 1.0, v13
	v_div_scale_f32 v35, s[2:3], v13, v13, v211
	v_rcp_f32_e32 v43, v35
	v_div_scale_f32 v44, vcc, v211, v13, v211
	v_fma_f32 v45, -v35, v43, 1.0
	v_fmac_f32_e32 v43, v45, v43
	v_mul_f32_e32 v45, v44, v43
	v_fma_f32 v46, -v35, v45, v44
	v_fmac_f32_e32 v45, v46, v43
	v_fma_f32 v35, -v35, v45, v44
	v_div_fmas_f32 v35, v35, v43, v45
	v_div_fixup_f32 v12, v35, v13, v211
	ds_write_b32 v34, v12
	v_add_u32_e32 v34, 0x800, v34
	v_mul_f32_e32 v13, 0xbfb8aa3b, v212
	v_exp_f32_e32 v13, v13
	s_nop 0
	v_add_f32_e32 v13, 1.0, v13
	v_div_scale_f32 v35, s[2:3], v13, v13, v212
	v_rcp_f32_e32 v43, v35
	v_div_scale_f32 v44, vcc, v212, v13, v212
	v_fma_f32 v45, -v35, v43, 1.0
	v_fmac_f32_e32 v43, v45, v43
	v_mul_f32_e32 v45, v44, v43
	v_fma_f32 v46, -v35, v45, v44
	v_fmac_f32_e32 v45, v46, v43
	v_fma_f32 v35, -v35, v45, v44
	v_div_fmas_f32 v35, v35, v43, v45
	v_div_fixup_f32 v12, v35, v13, v212
	ds_write_b32 v34, v12
	v_add_u32_e32 v34, 0x800, v34
	v_mul_f32_e32 v13, 0xbfb8aa3b, v213
	v_exp_f32_e32 v13, v13
	s_nop 0
	v_add_f32_e32 v13, 1.0, v13
	v_div_scale_f32 v35, s[2:3], v13, v13, v213
	v_rcp_f32_e32 v43, v35
	v_div_scale_f32 v44, vcc, v213, v13, v213
	v_fma_f32 v45, -v35, v43, 1.0
	v_fmac_f32_e32 v43, v45, v43
	v_mul_f32_e32 v45, v44, v43
	v_fma_f32 v46, -v35, v45, v44
	v_fmac_f32_e32 v45, v46, v43
; __device__ __forceinline__ void phase0(CArgs a, LAS unsigned char* lds, int tid, int lane, int wave, int G, int bx) {
;     ...
;             for (int idx = tid; idx < NB * 1024; idx += 512) { const int r = idx >> 10, k = idx & 1023;
;                 const float c = r < 2 ? a->in[7][r * D + half * 1024 + k] : a->in[8][(r - 2) * D + half * 1024 + k];
;                 S[idx] = c / (1.0f + __expf(-c)); }
	v_fma_f32 v35, -v35, v45, v44
	v_div_fmas_f32 v35, v35, v43, v45
	v_div_fixup_f32 v12, v35, v13, v213
	ds_write_b32 v34, v12
	v_add_u32_e32 v34, 0x800, v34
	v_mul_f32_e32 v13, 0xbfb8aa3b, v220
	v_exp_f32_e32 v13, v13
	s_nop 0
	v_add_f32_e32 v13, 1.0, v13
	v_div_scale_f32 v35, s[2:3], v13, v13, v220
	v_rcp_f32_e32 v43, v35
	v_div_scale_f32 v44, vcc, v220, v13, v220
	v_fma_f32 v45, -v35, v43, 1.0
	v_fmac_f32_e32 v43, v45, v43
	v_mul_f32_e32 v45, v44, v43
	v_fma_f32 v46, -v35, v45, v44
	v_fmac_f32_e32 v45, v46, v43
	v_fma_f32 v35, -v35, v45, v44
	v_div_fmas_f32 v35, v35, v43, v45
	v_div_fixup_f32 v12, v35, v13, v220
	ds_write_b32 v34, v12
	v_add_u32_e32 v34, 0x800, v34
	v_mul_f32_e32 v13, 0xbfb8aa3b, v221
	v_exp_f32_e32 v13, v13
	s_nop 0
	v_add_f32_e32 v13, 1.0, v13
	v_div_scale_f32 v35, s[2:3], v13, v13, v221
	v_rcp_f32_e32 v43, v35
	v_div_scale_f32 v44, vcc, v221, v13, v221
	v_fma_f32 v45, -v35, v43, 1.0
	v_fmac_f32_e32 v43, v45, v43
	v_mul_f32_e32 v45, v44, v43
	v_fma_f32 v46, -v35, v45, v44
	v_fmac_f32_e32 v45, v46, v43
	v_fma_f32 v35, -v35, v45, v44
	v_div_fmas_f32 v35, v35, v43, v45
	v_div_fixup_f32 v12, v35, v13, v221
	ds_write_b32 v34, v12
	v_add_u32_e32 v34, 0x800, v34
	v_mul_f32_e32 v13, 0xbfb8aa3b, v222
	v_exp_f32_e32 v13, v13
	s_nop 0
	v_add_f32_e32 v13, 1.0, v13
	v_div_scale_f32 v35, s[2:3], v13, v13, v222
	v_rcp_f32_e32 v43, v35
	v_div_scale_f32 v44, vcc, v222, v13, v222
	v_fma_f32 v45, -v35, v43, 1.0
	v_fmac_f32_e32 v43, v45, v43
	v_mul_f32_e32 v45, v44, v43
	v_fma_f32 v46, -v35, v45, v44
	v_fmac_f32_e32 v45, v46, v43
	v_fma_f32 v35, -v35, v45, v44
	v_div_fmas_f32 v35, v35, v43, v45
	v_div_fixup_f32 v12, v35, v13, v222
	ds_write_b32 v34, v12
	v_add_u32_e32 v34, 0x800, v34
	v_mul_f32_e32 v13, 0xbfb8aa3b, v223
	v_exp_f32_e32 v13, v13
	s_nop 0
	v_add_f32_e32 v13, 1.0, v13
	v_div_scale_f32 v35, s[2:3], v13, v13, v223
	v_rcp_f32_e32 v43, v35
	v_div_scale_f32 v44, vcc, v223, v13, v223
	v_fma_f32 v45, -v35, v43, 1.0
	v_fmac_f32_e32 v43, v45, v43
	v_mul_f32_e32 v45, v44, v43
	v_fma_f32 v46, -v35, v45, v44
	v_fmac_f32_e32 v45, v46, v43
	v_fma_f32 v35, -v35, v45, v44
	v_div_fmas_f32 v35, v35, v43, v45
	v_div_fixup_f32 v12, v35, v13, v223
	ds_write_b32 v34, v12
	v_add_u32_e32 v34, 0x800, v34
	v_mul_f32_e32 v13, 0xbfb8aa3b, v224
	v_exp_f32_e32 v13, v13
	s_nop 0
	v_add_f32_e32 v13, 1.0, v13
	v_div_scale_f32 v35, s[2:3], v13, v13, v224
	v_rcp_f32_e32 v43, v35
	v_div_scale_f32 v44, vcc, v224, v13, v224
	v_fma_f32 v45, -v35, v43, 1.0
	v_fmac_f32_e32 v43, v45, v43
	v_mul_f32_e32 v45, v44, v43
	v_fma_f32 v46, -v35, v45, v44
	v_fmac_f32_e32 v45, v46, v43
	v_fma_f32 v35, -v35, v45, v44
	v_div_fmas_f32 v35, v35, v43, v45
	v_div_fixup_f32 v12, v35, v13, v224
	ds_write_b32 v34, v12
	v_add_u32_e32 v34, 0x800, v34
	v_mul_f32_e32 v13, 0xbfb8aa3b, v225
	v_exp_f32_e32 v13, v13
	s_nop 0
	v_add_f32_e32 v13, 1.0, v13
	v_div_scale_f32 v35, s[2:3], v13, v13, v225
	v_rcp_f32_e32 v43, v35
	v_div_scale_f32 v44, vcc, v225, v13, v225
	v_fma_f32 v45, -v35, v43, 1.0
	v_fmac_f32_e32 v43, v45, v43
	v_mul_f32_e32 v45, v44, v43
	v_fma_f32 v46, -v35, v45, v44
	v_fmac_f32_e32 v45, v46, v43
	v_fma_f32 v35, -v35, v45, v44
	v_div_fmas_f32 v35, v35, v43, v45
	v_div_fixup_f32 v12, v35, v13, v225
	ds_write_b32 v34, v12
	v_add_u32_e32 v34, 0x800, v34
	v_mul_f32_e32 v13, 0xbfb8aa3b, v226
	v_exp_f32_e32 v13, v13
	s_nop 0
	v_add_f32_e32 v13, 1.0, v13
	v_div_scale_f32 v35, s[2:3], v13, v13, v226
	v_rcp_f32_e32 v43, v35
	v_div_scale_f32 v44, vcc, v226, v13, v226
	v_fma_f32 v45, -v35, v43, 1.0
	v_fmac_f32_e32 v43, v45, v43
	v_mul_f32_e32 v45, v44, v43
	v_fma_f32 v46, -v35, v45, v44
	v_fmac_f32_e32 v45, v46, v43
	v_fma_f32 v35, -v35, v45, v44
	v_div_fmas_f32 v35, v35, v43, v45
	v_div_fixup_f32 v12, v35, v13, v226
	ds_write_b32 v34, v12
	v_add_u32_e32 v34, 0x800, v34
	v_mul_f32_e32 v13, 0xbfb8aa3b, v227
	v_exp_f32_e32 v13, v13
	s_nop 0
	v_add_f32_e32 v13, 1.0, v13
	v_div_scale_f32 v35, s[2:3], v13, v13, v227
	v_rcp_f32_e32 v43, v35
	v_div_scale_f32 v44, vcc, v227, v13, v227
	v_fma_f32 v45, -v35, v43, 1.0
	v_fmac_f32_e32 v43, v45, v43
	v_mul_f32_e32 v45, v44, v43
	v_fma_f32 v46, -v35, v45, v44
	v_fmac_f32_e32 v45, v46, v43
	v_fma_f32 v35, -v35, v45, v44
	v_div_fmas_f32 v35, v35, v43, v45
	v_div_fixup_f32 v12, v35, v13, v227
	ds_write_b32 v34, v12
	v_add_u32_e32 v34, 0x800, v34
	v_mul_f32_e32 v13, 0xbfb8aa3b, v228
	v_exp_f32_e32 v13, v13
	s_nop 0
	v_add_f32_e32 v13, 1.0, v13
	v_div_scale_f32 v35, s[2:3], v13, v13, v228
	v_rcp_f32_e32 v43, v35
	v_div_scale_f32 v44, vcc, v228, v13, v228
	v_fma_f32 v45, -v35, v43, 1.0
	v_fmac_f32_e32 v43, v45, v43
	v_mul_f32_e32 v45, v44, v43
	v_fma_f32 v46, -v35, v45, v44
	v_fmac_f32_e32 v45, v46, v43
	v_fma_f32 v35, -v35, v45, v44
	v_div_fmas_f32 v35, v35, v43, v45
	v_div_fixup_f32 v12, v35, v13, v228
	ds_write_b32 v34, v12
	v_add_u32_e32 v34, 0x800, v34
	v_mul_f32_e32 v13, 0xbfb8aa3b, v229
	v_exp_f32_e32 v13, v13
	s_nop 0
	v_add_f32_e32 v13, 1.0, v13
	v_div_scale_f32 v35, s[2:3], v13, v13, v229
	v_rcp_f32_e32 v43, v35
	v_div_scale_f32 v44, vcc, v229, v13, v229
	v_fma_f32 v45, -v35, v43, 1.0
	v_fmac_f32_e32 v43, v45, v43
	v_mul_f32_e32 v45, v44, v43
	v_fma_f32 v46, -v35, v45, v44
	v_fmac_f32_e32 v45, v46, v43
	v_fma_f32 v35, -v35, v45, v44
	v_div_fmas_f32 v35, v35, v43, v45
	v_div_fixup_f32 v12, v35, v13, v229
	ds_write_b32 v34, v12
	v_add_u32_e32 v34, 0x800, v34
	v_mul_f32_e32 v13, 0xbfb8aa3b, v230
	v_exp_f32_e32 v13, v13
	s_nop 0
	v_add_f32_e32 v13, 1.0, v13
	v_div_scale_f32 v35, s[2:3], v13, v13, v230
	v_rcp_f32_e32 v43, v35
	v_div_scale_f32 v44, vcc, v230, v13, v230
	v_fma_f32 v45, -v35, v43, 1.0
	v_fmac_f32_e32 v43, v45, v43
	v_mul_f32_e32 v45, v44, v43
; __device__ __forceinline__ void phase0(CArgs a, LAS unsigned char* lds, int tid, int lane, int wave, int G, int bx) {
;     ...
;             for (int idx = tid; idx < NB * 1024; idx += 512) { const int r = idx >> 10, k = idx & 1023;
;                 const float c = r < 2 ? a->in[7][r * D + half * 1024 + k] : a->in[8][(r - 2) * D + half * 1024 + k];
;                 S[idx] = c / (1.0f + __expf(-c)); }
	v_fma_f32 v46, -v35, v45, v44
	v_fmac_f32_e32 v45, v46, v43
	v_fma_f32 v35, -v35, v45, v44
	v_div_fmas_f32 v35, v35, v43, v45
	v_div_fixup_f32 v12, v35, v13, v230
	ds_write_b32 v34, v12
	v_add_u32_e32 v34, 0x800, v34
	v_mul_f32_e32 v13, 0xbfb8aa3b, v231
	v_exp_f32_e32 v13, v13
	s_nop 0
	v_add_f32_e32 v13, 1.0, v13
	v_div_scale_f32 v35, s[2:3], v13, v13, v231
	v_rcp_f32_e32 v43, v35
	v_div_scale_f32 v44, vcc, v231, v13, v231
	v_fma_f32 v45, -v35, v43, 1.0
	v_fmac_f32_e32 v43, v45, v43
	v_mul_f32_e32 v45, v44, v43
	v_fma_f32 v46, -v35, v45, v44
	v_fmac_f32_e32 v45, v46, v43
	v_fma_f32 v35, -v35, v45, v44
	v_div_fmas_f32 v35, v35, v43, v45
	v_div_fixup_f32 v12, v35, v13, v231
	ds_write_b32 v34, v12
	v_add_u32_e32 v34, 0x800, v34
	v_mul_f32_e32 v13, 0xbfb8aa3b, v232
	v_exp_f32_e32 v13, v13
	s_nop 0
	v_add_f32_e32 v13, 1.0, v13
	v_div_scale_f32 v35, s[2:3], v13, v13, v232
	v_rcp_f32_e32 v43, v35
	v_div_scale_f32 v44, vcc, v232, v13, v232
	v_fma_f32 v45, -v35, v43, 1.0
	v_fmac_f32_e32 v43, v45, v43
	v_mul_f32_e32 v45, v44, v43
	v_fma_f32 v46, -v35, v45, v44
	v_fmac_f32_e32 v45, v46, v43
	v_fma_f32 v35, -v35, v45, v44
	v_div_fmas_f32 v35, v35, v43, v45
	v_div_fixup_f32 v12, v35, v13, v232
	ds_write_b32 v34, v12
	v_add_u32_e32 v34, 0x800, v34
	v_mul_f32_e32 v13, 0xbfb8aa3b, v233
	v_exp_f32_e32 v13, v13
	s_nop 0
	v_add_f32_e32 v13, 1.0, v13
	v_div_scale_f32 v35, s[2:3], v13, v13, v233
	v_rcp_f32_e32 v43, v35
	v_div_scale_f32 v44, vcc, v233, v13, v233
	v_fma_f32 v45, -v35, v43, 1.0
	v_fmac_f32_e32 v43, v45, v43
	v_mul_f32_e32 v45, v44, v43
	v_fma_f32 v46, -v35, v45, v44
	v_fmac_f32_e32 v45, v46, v43
	v_fma_f32 v35, -v35, v45, v44
	v_div_fmas_f32 v35, v35, v43, v45
	v_div_fixup_f32 v12, v35, v13, v233
	ds_write_b32 v34, v12
	v_add_u32_e32 v34, 0x800, v34
	v_mul_f32_e32 v13, 0xbfb8aa3b, v234
	v_exp_f32_e32 v13, v13
	s_nop 0
	v_add_f32_e32 v13, 1.0, v13
	v_div_scale_f32 v35, s[2:3], v13, v13, v234
	v_rcp_f32_e32 v43, v35
	v_div_scale_f32 v44, vcc, v234, v13, v234
	v_fma_f32 v45, -v35, v43, 1.0
	v_fmac_f32_e32 v43, v45, v43
	v_mul_f32_e32 v45, v44, v43
	v_fma_f32 v46, -v35, v45, v44
	v_fmac_f32_e32 v45, v46, v43
	v_fma_f32 v35, -v35, v45, v44
	v_div_fmas_f32 v35, v35, v43, v45
	v_div_fixup_f32 v12, v35, v13, v234
	ds_write_b32 v34, v12
	v_add_u32_e32 v34, 0x800, v34
	v_mul_f32_e32 v13, 0xbfb8aa3b, v235
	v_exp_f32_e32 v13, v13
	s_nop 0
	v_add_f32_e32 v13, 1.0, v13
	v_div_scale_f32 v35, s[2:3], v13, v13, v235
	v_rcp_f32_e32 v43, v35
	v_div_scale_f32 v44, vcc, v235, v13, v235
	v_fma_f32 v45, -v35, v43, 1.0
	v_fmac_f32_e32 v43, v45, v43
	v_mul_f32_e32 v45, v44, v43
	v_fma_f32 v46, -v35, v45, v44
	v_fmac_f32_e32 v45, v46, v43
	v_fma_f32 v35, -v35, v45, v44
	v_div_fmas_f32 v35, v35, v43, v45
	v_div_fixup_f32 v12, v35, v13, v235
	ds_write_b32 v34, v12
	v_add_u32_e32 v34, 0x800, v34
	v_mul_f32_e32 v13, 0xbfb8aa3b, v236
	v_exp_f32_e32 v13, v13
	s_nop 0
	v_add_f32_e32 v13, 1.0, v13
	v_div_scale_f32 v35, s[2:3], v13, v13, v236
	v_rcp_f32_e32 v43, v35
	v_div_scale_f32 v44, vcc, v236, v13, v236
	v_fma_f32 v45, -v35, v43, 1.0
	v_fmac_f32_e32 v43, v45, v43
	v_mul_f32_e32 v45, v44, v43
	v_fma_f32 v46, -v35, v45, v44
	v_fmac_f32_e32 v45, v46, v43
	v_fma_f32 v35, -v35, v45, v44
	v_div_fmas_f32 v35, v35, v43, v45
	v_div_fixup_f32 v12, v35, v13, v236
	ds_write_b32 v34, v12
	v_add_u32_e32 v34, 0x800, v34
	v_mul_f32_e32 v13, 0xbfb8aa3b, v237
	v_exp_f32_e32 v13, v13
	s_nop 0
	v_add_f32_e32 v13, 1.0, v13
	v_div_scale_f32 v35, s[2:3], v13, v13, v237
	v_rcp_f32_e32 v43, v35
	v_div_scale_f32 v44, vcc, v237, v13, v237
	v_fma_f32 v45, -v35, v43, 1.0
	v_fmac_f32_e32 v43, v45, v43
	v_mul_f32_e32 v45, v44, v43
	v_fma_f32 v46, -v35, v45, v44
	v_fmac_f32_e32 v45, v46, v43
	v_fma_f32 v35, -v35, v45, v44
	v_div_fmas_f32 v35, v35, v43, v45
	v_div_fixup_f32 v12, v35, v13, v237
	ds_write_b32 v34, v12
	v_add_u32_e32 v34, 0x800, v34
	v_mul_f32_e32 v13, 0xbfb8aa3b, v238
	v_exp_f32_e32 v13, v13
	s_nop 0
	v_add_f32_e32 v13, 1.0, v13
	v_div_scale_f32 v35, s[2:3], v13, v13, v238
; __device__ __forceinline__ void phase0(CArgs a, LAS unsigned char* lds, int tid, int lane, int wave, int G, int bx) {
;     ...
;             for (int idx = tid; idx < NB * 1024; idx += 512) { const int r = idx >> 10, k = idx & 1023;
;                 const float c = r < 2 ? a->in[7][r * D + half * 1024 + k] : a->in[8][(r - 2) * D + half * 1024 + k];
;                 S[idx] = c / (1.0f + __expf(-c)); }
	v_rcp_f32_e32 v43, v35
	v_div_scale_f32 v44, vcc, v238, v13, v238
	v_fma_f32 v45, -v35, v43, 1.0
	v_fmac_f32_e32 v43, v45, v43
	v_mul_f32_e32 v45, v44, v43
	v_fma_f32 v46, -v35, v45, v44
	v_fmac_f32_e32 v45, v46, v43
	v_fma_f32 v35, -v35, v45, v44
	v_div_fmas_f32 v35, v35, v43, v45
	v_div_fixup_f32 v12, v35, v13, v238
	ds_write_b32 v34, v12
	v_add_u32_e32 v34, 0x800, v34
	v_mul_f32_e32 v13, 0xbfb8aa3b, v239
	v_exp_f32_e32 v13, v13
	s_nop 0
	v_add_f32_e32 v13, 1.0, v13
	v_div_scale_f32 v35, s[2:3], v13, v13, v239
	v_rcp_f32_e32 v43, v35
	v_div_scale_f32 v44, vcc, v239, v13, v239
	v_fma_f32 v45, -v35, v43, 1.0
	v_fmac_f32_e32 v43, v45, v43
	v_mul_f32_e32 v45, v44, v43
	v_fma_f32 v46, -v35, v45, v44
	v_fmac_f32_e32 v45, v46, v43
	v_fma_f32 v35, -v35, v45, v44
	v_div_fmas_f32 v35, v35, v43, v45
	v_div_fixup_f32 v12, v35, v13, v239
	ds_write_b32 v34, v12
	v_add_u32_e32 v34, 0x800, v34
	v_mul_f32_e32 v13, 0xbfb8aa3b, v240
	v_exp_f32_e32 v13, v13
	s_nop 0
	v_add_f32_e32 v13, 1.0, v13
	v_div_scale_f32 v35, s[2:3], v13, v13, v240
	v_rcp_f32_e32 v43, v35
	v_div_scale_f32 v44, vcc, v240, v13, v240
	v_fma_f32 v45, -v35, v43, 1.0
	v_fmac_f32_e32 v43, v45, v43
	v_mul_f32_e32 v45, v44, v43
	v_fma_f32 v46, -v35, v45, v44
	v_fmac_f32_e32 v45, v46, v43
	v_fma_f32 v35, -v35, v45, v44
	v_div_fmas_f32 v35, v35, v43, v45
	v_div_fixup_f32 v12, v35, v13, v240
	ds_write_b32 v34, v12
	v_add_u32_e32 v34, 0x800, v34
	v_mul_f32_e32 v13, 0xbfb8aa3b, v241
	v_exp_f32_e32 v13, v13
	s_nop 0
	v_add_f32_e32 v13, 1.0, v13
	v_div_scale_f32 v35, s[2:3], v13, v13, v241
	v_rcp_f32_e32 v43, v35
	v_div_scale_f32 v44, vcc, v241, v13, v241
	v_fma_f32 v45, -v35, v43, 1.0
	v_fmac_f32_e32 v43, v45, v43
	v_mul_f32_e32 v45, v44, v43
	v_fma_f32 v46, -v35, v45, v44
	v_fmac_f32_e32 v45, v46, v43
	v_fma_f32 v35, -v35, v45, v44
	v_div_fmas_f32 v35, v35, v43, v45
	v_div_fixup_f32 v12, v35, v13, v241
	ds_write_b32 v34, v12
	v_add_u32_e32 v34, 0x800, v34
	v_mul_f32_e32 v13, 0xbfb8aa3b, v242
	v_exp_f32_e32 v13, v13
	s_nop 0
	v_add_f32_e32 v13, 1.0, v13
	v_div_scale_f32 v35, s[2:3], v13, v13, v242
	v_rcp_f32_e32 v43, v35
	v_div_scale_f32 v44, vcc, v242, v13, v242
	v_fma_f32 v45, -v35, v43, 1.0
	v_fmac_f32_e32 v43, v45, v43
	v_mul_f32_e32 v45, v44, v43
	v_fma_f32 v46, -v35, v45, v44
	v_fmac_f32_e32 v45, v46, v43
	v_fma_f32 v35, -v35, v45, v44
	v_div_fmas_f32 v35, v35, v43, v45
	v_div_fixup_f32 v12, v35, v13, v242
	ds_write_b32 v34, v12
	v_add_u32_e32 v34, 0x800, v34
	v_mul_f32_e32 v13, 0xbfb8aa3b, v243
	v_exp_f32_e32 v13, v13
	s_nop 0
	v_add_f32_e32 v13, 1.0, v13
	v_div_scale_f32 v35, s[2:3], v13, v13, v243
	v_rcp_f32_e32 v43, v35
	v_div_scale_f32 v44, vcc, v243, v13, v243
	v_fma_f32 v45, -v35, v43, 1.0
	v_fmac_f32_e32 v43, v45, v43
	v_mul_f32_e32 v45, v44, v43
	v_fma_f32 v46, -v35, v45, v44
	v_fmac_f32_e32 v45, v46, v43
	v_fma_f32 v35, -v35, v45, v44
	v_div_fmas_f32 v35, v35, v43, v45
	v_div_fixup_f32 v12, v35, v13, v243
	ds_write_b32 v34, v12
	v_add_u32_e32 v34, 0x800, v34
	v_mul_f32_e32 v13, 0xbfb8aa3b, v244
	v_exp_f32_e32 v13, v13
	s_nop 0
	v_add_f32_e32 v13, 1.0, v13
	v_div_scale_f32 v35, s[2:3], v13, v13, v244
	v_rcp_f32_e32 v43, v35
	v_div_scale_f32 v44, vcc, v244, v13, v244
	v_fma_f32 v45, -v35, v43, 1.0
	v_fmac_f32_e32 v43, v45, v43
	v_mul_f32_e32 v45, v44, v43
	v_fma_f32 v46, -v35, v45, v44
	v_fmac_f32_e32 v45, v46, v43
	v_fma_f32 v35, -v35, v45, v44
	v_div_fmas_f32 v35, v35, v43, v45
	v_div_fixup_f32 v12, v35, v13, v244
	ds_write_b32 v34, v12
	v_add_u32_e32 v34, 0x800, v34
	v_mul_f32_e32 v13, 0xbfb8aa3b, v245
	v_exp_f32_e32 v13, v13
	s_nop 0
	v_add_f32_e32 v13, 1.0, v13
	v_div_scale_f32 v35, s[2:3], v13, v13, v245
	v_rcp_f32_e32 v43, v35
	v_div_scale_f32 v44, vcc, v245, v13, v245
	v_fma_f32 v45, -v35, v43, 1.0
	v_fmac_f32_e32 v43, v45, v43
	v_mul_f32_e32 v45, v44, v43
	v_fma_f32 v46, -v35, v45, v44
	v_fmac_f32_e32 v45, v46, v43
	v_fma_f32 v35, -v35, v45, v44
	v_div_fmas_f32 v35, v35, v43, v45
	v_div_fixup_f32 v12, v35, v13, v245
	ds_write_b32 v34, v12
	v_add_u32_e32 v34, 0x800, v34
